# phase-4 branch-projection GEMM (formerly single-buffered register staging) now uses LDS-DMA double buffering with rolling fragment registers
# speedup vs baseline: 1.0826x; 1.0145x over previous
.LBB0_127:
	v_mul_f32_e32 v48, 0xbfb8aa3b, v48
	v_exp_f32_e32 v48, v48
	s_nop 0
	v_mul_f32_e32 v16, 0xbfb8aa3b, v16
	v_exp_f32_e32 v16, v16
	v_mul_f32_e32 v17, 0xbfb8aa3b, v17
	v_mul_f32_e32 v49, 0xbfb8aa3b, v49
	v_add_f32_e32 v48, 1.0, v48
	v_exp_f32_e32 v17, v17
	v_exp_f32_e32 v49, v49
	s_waitcnt vmcnt(3)
	v_rcp_f32_e32 v74, v48
	v_mul_f32_e32 v48, 0xbfb8aa3b, v50
	v_mul_f32_e32 v32, 0xbfb8aa3b, v32
	v_exp_f32_e32 v48, v48
	v_mul_f32_e32 v50, 0xbfb8aa3b, v51
	v_exp_f32_e32 v32, v32
	v_mul_f32_e32 v33, 0xbfb8aa3b, v33
	v_exp_f32_e32 v50, v50
	v_exp_f32_e32 v33, v33
	v_add_f32_e32 v16, 1.0, v16
	v_rcp_f32_e32 v106, v16
	v_add_f32_e32 v16, 1.0, v17
	v_mul_f32_e32 v17, 0xbfb8aa3b, v18
	v_add_f32_e32 v49, 1.0, v49
	v_exp_f32_e32 v17, v17
	v_mul_f32_e32 v18, 0xbfb8aa3b, v19
	v_rcp_f32_e32 v75, v49
	v_add_f32_e32 v48, 1.0, v48
	v_mul_f32_e32 v49, 0xbfb8aa3b, v52
	v_add_f32_e32 v32, 1.0, v32
	v_exp_f32_e32 v18, v18
	v_rcp_f32_e32 v76, v48
	v_add_f32_e32 v48, 1.0, v50
	v_exp_f32_e32 v49, v49
	v_mul_f32_e32 v50, 0xbfb8aa3b, v53
	s_waitcnt vmcnt(1)
	v_rcp_f32_e32 v90, v32
	v_add_f32_e32 v32, 1.0, v33
	v_mul_f32_e32 v33, 0xbfb8aa3b, v34
	v_exp_f32_e32 v50, v50
	v_exp_f32_e32 v33, v33
	v_mul_f32_e32 v34, 0xbfb8aa3b, v35
	v_exp_f32_e32 v34, v34
	v_rcp_f32_e32 v107, v16
	v_add_f32_e32 v16, 1.0, v17
	v_mul_f32_e32 v17, 0xbfb8aa3b, v20
	v_rcp_f32_e32 v108, v16
	v_add_f32_e32 v16, 1.0, v18
	v_exp_f32_e32 v17, v17
	v_mul_f32_e32 v18, 0xbfb8aa3b, v21
	v_rcp_f32_e32 v77, v48
	v_add_f32_e32 v48, 1.0, v49
	v_mul_f32_e32 v49, 0xbfb8aa3b, v54
	v_exp_f32_e32 v18, v18
	v_rcp_f32_e32 v78, v48
	v_add_f32_e32 v48, 1.0, v50
	v_exp_f32_e32 v49, v49
	v_mul_f32_e32 v50, 0xbfb8aa3b, v55
	v_rcp_f32_e32 v91, v32
	v_add_f32_e32 v32, 1.0, v33
	v_mul_f32_e32 v33, 0xbfb8aa3b, v36
	v_exp_f32_e32 v50, v50
	s_waitcnt vmcnt(0)
	v_rcp_f32_e32 v92, v32
	v_add_f32_e32 v32, 1.0, v34
	v_exp_f32_e32 v33, v33
	v_mul_f32_e32 v34, 0xbfb8aa3b, v37
	v_exp_f32_e32 v34, v34
	v_rcp_f32_e32 v109, v16
	v_add_f32_e32 v16, 1.0, v17
	v_mul_f32_e32 v17, 0xbfb8aa3b, v22
	v_rcp_f32_e32 v110, v16
	v_add_f32_e32 v16, 1.0, v18
	v_exp_f32_e32 v17, v17
	v_mul_f32_e32 v18, 0xbfb8aa3b, v23
	v_rcp_f32_e32 v79, v48
	v_add_f32_e32 v48, 1.0, v49
	v_mul_f32_e32 v49, 0xbfb8aa3b, v56
	v_exp_f32_e32 v18, v18
	v_rcp_f32_e32 v80, v48
	v_add_f32_e32 v48, 1.0, v50
	v_exp_f32_e32 v49, v49
	v_mul_f32_e32 v50, 0xbfb8aa3b, v57
	v_rcp_f32_e32 v93, v32
	v_add_f32_e32 v32, 1.0, v33
	v_mul_f32_e32 v33, 0xbfb8aa3b, v38
	v_exp_f32_e32 v50, v50
	v_rcp_f32_e32 v94, v32
	v_add_f32_e32 v32, 1.0, v34
	v_exp_f32_e32 v33, v33
	v_mul_f32_e32 v34, 0xbfb8aa3b, v39
	v_exp_f32_e32 v34, v34
	v_rcp_f32_e32 v111, v16
	v_add_f32_e32 v16, 1.0, v17
	v_mul_f32_e32 v17, 0xbfb8aa3b, v24
	v_rcp_f32_e32 v112, v16
	v_add_f32_e32 v16, 1.0, v18
	v_exp_f32_e32 v17, v17
	v_mul_f32_e32 v18, 0xbfb8aa3b, v25
	v_rcp_f32_e32 v81, v48
	v_add_f32_e32 v48, 1.0, v49
	v_mul_f32_e32 v49, 0xbfb8aa3b, v58
	v_exp_f32_e32 v18, v18
	v_rcp_f32_e32 v82, v48
	v_add_f32_e32 v48, 1.0, v50
	v_exp_f32_e32 v49, v49
	v_mul_f32_e32 v50, 0xbfb8aa3b, v59
	v_rcp_f32_e32 v95, v32
	v_add_f32_e32 v32, 1.0, v33
	v_mul_f32_e32 v33, 0xbfb8aa3b, v40
	v_exp_f32_e32 v50, v50
	v_rcp_f32_e32 v96, v32
	v_add_f32_e32 v32, 1.0, v34
	v_exp_f32_e32 v33, v33
	v_mul_f32_e32 v34, 0xbfb8aa3b, v41
	v_exp_f32_e32 v34, v34
	v_rcp_f32_e32 v113, v16
	v_add_f32_e32 v16, 1.0, v17
	v_mul_f32_e32 v17, 0xbfb8aa3b, v26
	v_rcp_f32_e32 v114, v16
	v_add_f32_e32 v16, 1.0, v18
	v_exp_f32_e32 v17, v17
	v_mul_f32_e32 v18, 0xbfb8aa3b, v27
	v_rcp_f32_e32 v83, v48
	v_add_f32_e32 v48, 1.0, v49
	v_mul_f32_e32 v49, 0xbfb8aa3b, v60
	v_exp_f32_e32 v18, v18
	v_rcp_f32_e32 v84, v48
	v_add_f32_e32 v48, 1.0, v50
	v_exp_f32_e32 v49, v49
	v_mul_f32_e32 v50, 0xbfb8aa3b, v61
	v_rcp_f32_e32 v97, v32
	v_add_f32_e32 v32, 1.0, v33
	v_mul_f32_e32 v33, 0xbfb8aa3b, v42
	v_exp_f32_e32 v50, v50
	v_rcp_f32_e32 v98, v32
	v_add_f32_e32 v32, 1.0, v34
	v_exp_f32_e32 v33, v33
	v_mul_f32_e32 v34, 0xbfb8aa3b, v43
	v_exp_f32_e32 v34, v34
	v_rcp_f32_e32 v115, v16
	v_add_f32_e32 v16, 1.0, v17
	v_mul_f32_e32 v17, 0xbfb8aa3b, v28
	s_cmp_eq_u32 s20, 1
	s_movk_i32 s2, 0x600
	s_movk_i32 s8, 0x108
	v_rcp_f32_e32 v116, v16
	v_add_f32_e32 v16, 1.0, v18
	v_exp_f32_e32 v17, v17
	v_mul_f32_e32 v18, 0xbfb8aa3b, v29
	s_cselect_b32 s2, 0x400, s2
	s_cselect_b32 s8, s8, 0x110
	s_cmp_eq_u32 s20, 0
	v_rcp_f32_e32 v85, v48
	v_add_f32_e32 v48, 1.0, v49
	v_mul_f32_e32 v49, 0xbfb8aa3b, v62
	v_exp_f32_e32 v18, v18
	s_cselect_b32 s8, 0x100, s8
	s_movk_i32 s9, 0x380
	v_rcp_f32_e32 v86, v48
	v_add_f32_e32 v48, 1.0, v50
	v_exp_f32_e32 v49, v49
	v_mul_f32_e32 v50, 0xbfb8aa3b, v63
	v_rcp_f32_e32 v99, v32
	v_add_f32_e32 v32, 1.0, v33
	v_mul_f32_e32 v33, 0xbfb8aa3b, v44
	s_cselect_b32 s2, 0, s2
	s_cselect_b32 s11, 10, 9
	s_cselect_b32 s10, 0x780, s9
	s_add_u32 s8, s52, s8
	v_exp_f32_e32 v50, v50
	v_rcp_f32_e32 v100, v32
	v_add_f32_e32 v32, 1.0, v34
	v_exp_f32_e32 v33, v33
	v_mul_f32_e32 v34, 0xbfb8aa3b, v45
	s_addc_u32 s9, s53, 0
	v_exp_f32_e32 v34, v34
	v_rcp_f32_e32 v117, v16
	v_add_f32_e32 v16, 1.0, v17
	s_load_dwordx2 s[8:9], s[8:9], 0x0
	v_rcp_f32_e32 v118, v16
	v_add_f32_e32 v16, 1.0, v18
	s_lshl_b32 s21, s2, 1
	v_rcp_f32_e32 v87, v48
	v_add_f32_e32 v48, 1.0, v49
	v_rcp_f32_e32 v119, v16
	v_mul_f32_e32 v16, 0xbfb8aa3b, v30
	s_add_u32 s22, s16, s21
	v_rcp_f32_e32 v88, v48
	v_add_f32_e32 v48, 1.0, v50
	v_rcp_f32_e32 v101, v32
	v_add_f32_e32 v32, 1.0, v33
	v_mul_f32_e32 v33, 0xbfb8aa3b, v46
	v_exp_f32_e32 v60, v16
	v_mul_f32_e32 v16, 0xbfb8aa3b, v31
	s_addc_u32 s23, s17, 0
	s_lshl_b64 s[24:25], s[4:5], s11
	v_mov_b32_e32 v62, v200
	v_rcp_f32_e32 v89, v48
	v_rcp_f32_e32 v102, v32
	v_add_f32_e32 v32, 1.0, v34
	v_exp_f32_e32 v33, v33
	v_mul_f32_e32 v34, 0xbfb8aa3b, v47
	v_exp_f32_e32 v61, v16
	s_lshl_b64 s[24:25], s[24:25], 1
	v_exp_f32_e32 v34, v34
	v_ashrrev_i32_e32 v48, 3, v62
	v_lshlrev_b32_e32 v16, 4, v62
	s_waitcnt lgkmcnt(0)
	s_add_u32 s8, s8, s24
	v_and_b32_e32 v196, 0x70, v16
	v_ashrrev_i32_e32 v49, 31, v48
	s_addc_u32 s9, s9, s25
	v_lshl_add_u64 v[40:41], s[22:23], 0, v[196:197]
	v_lshlrev_b64 v[50:51], 12, v[48:49]
	v_lshlrev_b64 v[20:21], s11, v[48:49]
	v_add_u32_e32 v28, 32, v48
	v_lshl_add_u64 v[44:45], s[8:9], 0, v[196:197]
	v_lshl_add_u64 v[16:17], v[40:41], 0, v[50:51]
	v_lshlrev_b64 v[52:53], 1, v[20:21]
	v_ashrrev_i32_e32 v29, 31, v28
	v_rcp_f32_e32 v103, v32
	v_add_f32_e32 v32, 1.0, v33
	v_and_b32_e32 v234, 63, v200
	v_readfirstlane_b32 s41, v200
	v_lshrrev_b32_e32 v235, 3, v234
	v_and_b32_e32 v236, 7, v234
	v_lshrrev_b32_e32 v237, 4, v234
	s_lshr_b32 s41, s41, 6
	v_xor_b32_e32 v236, v236, v237
	v_lshlrev_b32_e32 v236, 4, v236
	v_xor_b32_e32 v237, 64, v236
	s_lshl_b32 s32, s41, 5
	v_add_u32_e32 v235, s32, v235
	v_lshlrev_b32_e32 v238, 12, v235
	v_add_u32_e32 v194, v238, v236
	v_add_u32_e32 v201, v238, v237
	v_add_u32_e32 v201, 0x8000, v201
	s_add_u32 s32, s11, 1
	v_lshlrev_b32_e32 v238, s32, v235
	v_add_u32_e32 v206, v238, v236
	v_add_u32_e32 v212, v238, v237
	s_lshl_b32 s32, 8, s32
	v_add_u32_e32 v212, s32, v212
	s_mov_b32 s42, s22
	s_mov_b32 s43, s23
	s_add_u32 s44, s22, 0x10000
	s_addc_u32 s45, s23, 0
	s_mov_b32 s46, s8
	s_mov_b32 s47, s9
	s_lshl_b32 s32, s32, 1
	s_add_u32 s24, s8, s32
	s_addc_u32 s25, s9, 0
	v_and_b32_e32 v235, 31, v234
	v_lshrrev_b32_e32 v236, 5, v234
	v_bfe_u32 v237, v234, 1, 3
	v_xor_b32_e32 v236, v236, v237
	v_lshlrev_b32_e32 v236, 4, v236
	v_lshl_add_u32 v236, v235, 7, v236
	s_lshr_b32 s32, s41, 1
	s_lshl_b32 s32, s32, 13
	v_add_u32_e32 v213, s32, v236
	s_and_b32 s32, s41, 1
	s_lshl_b32 s32, s32, 13
	s_add_u32 s32, s32, 0x4000
	v_add_u32_e32 v214, s32, v236
	s_lshl_b32 s32, s41, 12
	s_lshr_b32 s41, s10, 7
	s_mov_b32 m0, s32
	s_nop 0
	global_load_lds_dwordx4 v194, s[42:43]
	s_add_u32 m0, m0, 0x400
	s_nop 0
	global_load_lds_dwordx4 v201, s[42:43]
	s_add_u32 m0, m0, 0x400
	s_nop 0
	global_load_lds_dwordx4 v194, s[44:45]
	s_add_u32 m0, m0, 0x400
	s_nop 0
	global_load_lds_dwordx4 v201, s[44:45]
	s_add_u32 m0, m0, 0x3400
	s_nop 0
	global_load_lds_dwordx4 v206, s[46:47]
	s_add_u32 m0, m0, 0x400
	s_nop 0
	global_load_lds_dwordx4 v212, s[46:47]
	s_add_u32 m0, m0, 0x400
	s_nop 0
	global_load_lds_dwordx4 v206, s[24:25]
	s_add_u32 m0, m0, 0x400
	s_nop 0
	global_load_lds_dwordx4 v212, s[24:25]
	s_add_u32 s42, s42, 128
	s_addc_u32 s43, s43, 0
	s_add_u32 s44, s44, 128
	s_addc_u32 s45, s45, 0
	s_add_u32 s46, s46, 128
	s_addc_u32 s47, s47, 0
	s_add_u32 s24, s24, 128
	s_addc_u32 s25, s25, 0
	s_mov_b32 s49, 0x8000
	v_lshl_add_u64 v[20:21], v[44:45], 0, v[52:53]
	v_lshlrev_b64 v[24:25], 12, v[28:29]
	v_lshlrev_b64 v[28:29], s11, v[28:29]
	v_add_u32_e32 v36, 64, v48
	v_rcp_f32_e32 v104, v32
	v_add_f32_e32 v32, 1.0, v34
	v_lshl_add_u64 v[24:25], v[40:41], 0, v[24:25]
	v_lshlrev_b64 v[54:55], 1, v[28:29]
	v_ashrrev_i32_e32 v37, 31, v36
	v_rcp_f32_e32 v105, v32
	v_lshl_add_u64 v[28:29], v[44:45], 0, v[54:55]
	v_lshlrev_b64 v[32:33], 12, v[36:37]
	v_lshlrev_b64 v[36:37], s11, v[36:37]
	v_add_u32_e32 v46, 0x60, v48
	v_lshl_add_u64 v[32:33], v[40:41], 0, v[32:33]
	v_lshlrev_b64 v[56:57], 1, v[36:37]
	v_ashrrev_i32_e32 v47, 31, v46
	v_lshl_add_u64 v[36:37], v[44:45], 0, v[56:57]
	v_lshlrev_b64 v[42:43], 12, v[46:47]
	v_lshlrev_b64 v[46:47], s11, v[46:47]
	v_lshl_add_u64 v[40:41], v[40:41], 0, v[42:43]
	v_lshlrev_b64 v[58:59], 1, v[46:47]
	v_lshl_add_u64 v[44:45], v[44:45], 0, v[58:59]
	v_mul_f32_e32 v0, 0xbfb8aa3b, v0
	v_exp_f32_e32 v0, v0
	v_mul_f32_e32 v1, 0xbfb8aa3b, v1
	v_exp_f32_e32 v1, v1
	s_movk_i32 s11, 0x90
	v_add_f32_e32 v0, 1.0, v0
	v_rcp_f32_e32 v125, v0
	v_add_f32_e32 v0, 1.0, v1
	v_mul_f32_e32 v1, 0xbfb8aa3b, v2
	v_exp_f32_e32 v1, v1
	v_mul_f32_e32 v2, 0xbfb8aa3b, v3
	v_exp_f32_e32 v2, v2
	v_rcp_f32_e32 v126, v0
	v_add_f32_e32 v0, 1.0, v1
	v_mul_f32_e32 v1, 0xbfb8aa3b, v4
	v_rcp_f32_e32 v127, v0
	v_add_f32_e32 v0, 1.0, v2
	v_exp_f32_e32 v1, v1
	v_mul_f32_e32 v2, 0xbfb8aa3b, v5
	v_exp_f32_e32 v2, v2
	v_rcp_f32_e32 v128, v0
	v_add_f32_e32 v0, 1.0, v1
	v_mul_f32_e32 v1, 0xbfb8aa3b, v6
	v_rcp_f32_e32 v129, v0
	v_add_f32_e32 v0, 1.0, v2
	v_exp_f32_e32 v1, v1
	v_mul_f32_e32 v2, 0xbfb8aa3b, v7
	v_exp_f32_e32 v2, v2
	v_rcp_f32_e32 v130, v0
	v_add_f32_e32 v0, 1.0, v1
	v_mul_f32_e32 v1, 0xbfb8aa3b, v8
	v_rcp_f32_e32 v131, v0
	v_add_f32_e32 v0, 1.0, v2
	v_exp_f32_e32 v1, v1
	v_mul_f32_e32 v2, 0xbfb8aa3b, v9
	v_exp_f32_e32 v2, v2
	v_rcp_f32_e32 v132, v0
	v_add_f32_e32 v0, 1.0, v1
	v_mul_f32_e32 v1, 0xbfb8aa3b, v10
	v_rcp_f32_e32 v133, v0
	v_add_f32_e32 v0, 1.0, v2
	v_exp_f32_e32 v1, v1
	v_mul_f32_e32 v2, 0xbfb8aa3b, v11
	v_exp_f32_e32 v2, v2
	v_rcp_f32_e32 v134, v0
	v_add_f32_e32 v0, 1.0, v1
	v_mul_f32_e32 v1, 0xbfb8aa3b, v12
	v_rcp_f32_e32 v135, v0
	v_add_f32_e32 v0, 1.0, v2
	v_exp_f32_e32 v1, v1
	v_mul_f32_e32 v2, 0xbfb8aa3b, v13
	v_exp_f32_e32 v2, v2
	v_rcp_f32_e32 v136, v0
	v_add_f32_e32 v0, 1.0, v1
	v_mul_f32_e32 v1, 0xbfb8aa3b, v14
	v_rcp_f32_e32 v137, v0
	v_add_f32_e32 v0, 1.0, v2
	v_exp_f32_e32 v1, v1
	v_mul_f32_e32 v2, 0xbfb8aa3b, v15
	v_exp_f32_e32 v2, v2
	v_rcp_f32_e32 v138, v0
	v_add_f32_e32 v0, 1.0, v1
	v_rcp_f32_e32 v139, v0
	v_add_f32_e32 v0, 1.0, v2
	v_add_u32_e32 v141, 0, v196
	v_mul_lo_u32 v142, v48, s11
	v_add_f32_e32 v49, 1.0, v60
	v_rcp_f32_e32 v140, v0
	v_add_u32_e32 v0, v141, v142
	v_rcp_f32_e32 v123, v49
	v_add_f32_e32 v49, 1.0, v61
	v_and_b32_e32 v0, 31, v62
	v_lshrrev_b32_e32 v1, 1, v62
	s_add_u32 s22, s18, s21
	v_rcp_f32_e32 v124, v49
	v_and_or_b32 v0, v1, s26, v0
	s_addc_u32 s23, s19, 0
	v_mul_lo_u32 v122, v0, s11
	v_and_b32_e32 v0, 0x5f, v62
	s_add_u32 s8, s8, 0x80
	v_mul_u32_u24_e32 v121, 0x90, v0
	v_or_b32_e32 v50, v50, v196
	v_or_b32_e32 v52, v52, v196
	s_addc_u32 s9, s9, 0
	v_or_b32_e32 v54, v54, v196
	v_or_b32_e32 v56, v56, v196
	v_or_b32_e32 v58, v58, v196
	v_mov_b32_e32 v0, 0
	s_mov_b32 s2, 0
	s_mov_b32 s40, 0xfffffc0
	v_and_b32_e32 v120, 16, v1
	v_lshl_add_u64 v[64:65], s[22:23], 0, v[50:51]
	v_lshl_add_u64 v[66:67], s[8:9], 0, v[52:53]
	v_lshl_add_u64 v[68:69], s[8:9], 0, v[54:55]
	v_lshl_add_u64 v[70:71], s[8:9], 0, v[56:57]
	v_lshl_add_u64 v[72:73], s[8:9], 0, v[58:59]
	s_mov_b64 s[8:9], 0
	v_mov_b32_e32 v1, v0
	v_mov_b32_e32 v2, v0
	v_mov_b32_e32 v3, v0
	v_mov_b32_e32 v4, v0
	v_mov_b32_e32 v5, v0
	v_mov_b32_e32 v6, v0
	v_mov_b32_e32 v7, v0
	v_mov_b32_e32 v8, v0
	v_mov_b32_e32 v9, v0
	v_mov_b32_e32 v10, v0
	v_mov_b32_e32 v11, v0
	v_mov_b32_e32 v12, v0
	v_mov_b32_e32 v13, v0
	v_mov_b32_e32 v14, v0
	v_mov_b32_e32 v15, v0
	v_mov_b32_e32 v16, v0
	v_mov_b32_e32 v17, v0
	v_mov_b32_e32 v18, v0
	v_mov_b32_e32 v19, v0
	v_mov_b32_e32 v20, v0
	v_mov_b32_e32 v21, v0
	v_mov_b32_e32 v22, v0
	v_mov_b32_e32 v23, v0
	v_mov_b32_e32 v24, v0
	v_mov_b32_e32 v25, v0
	v_mov_b32_e32 v26, v0
	v_mov_b32_e32 v27, v0
	v_mov_b32_e32 v28, v0
	v_mov_b32_e32 v29, v0
	v_mov_b32_e32 v30, v0
	v_mov_b32_e32 v31, v0
	v_mov_b32_e32 v32, v0
	v_mov_b32_e32 v33, v0
	v_mov_b32_e32 v34, v0
	v_mov_b32_e32 v35, v0
	v_mov_b32_e32 v36, v0
	v_mov_b32_e32 v37, v0
	v_mov_b32_e32 v38, v0
	v_mov_b32_e32 v39, v0
	v_mov_b32_e32 v40, v0
	v_mov_b32_e32 v41, v0
	v_mov_b32_e32 v42, v0
	v_mov_b32_e32 v43, v0
	v_mov_b32_e32 v44, v0
	v_mov_b32_e32 v45, v0
	v_mov_b32_e32 v46, v0
	v_mov_b32_e32 v47, v0
	v_mov_b32_e32 v48, v0
	v_mov_b32_e32 v49, v0
	v_mov_b32_e32 v50, v0
	v_mov_b32_e32 v51, v0
	v_mov_b32_e32 v52, v0
	v_mov_b32_e32 v53, v0
	v_mov_b32_e32 v54, v0
	v_mov_b32_e32 v55, v0
	v_mov_b32_e32 v56, v0
	v_mov_b32_e32 v57, v0
	v_mov_b32_e32 v58, v0
	v_mov_b32_e32 v59, v0
	v_mov_b32_e32 v60, v0
	v_mov_b32_e32 v61, v0
	v_mov_b32_e32 v62, v0
	v_mov_b32_e32 v63, v0
	s_mov_b32 s22, 0x20000
	s_waitcnt vmcnt(0)
	s_waitcnt lgkmcnt(0)
	s_barrier
.LBB0_128:
	ds_read_b128 v[144:147], v214
	ds_read_b128 v[182:185], v213
	ds_read_b128 v[186:189], v214 offset:4096
	ds_read_b128 v[190:193], v213 offset:4096
	v_xor_b32_e32 v242, 32, v213
	v_xor_b32_e32 v243, 32, v214
	ds_read_b128 v[202:205], v243
	ds_read_b128 v[208:211], v242
	ds_read_b128 v[234:237], v243 offset:4096
	ds_read_b128 v[238:241], v242 offset:4096
	s_add_u32 m0, s32, s49
	s_nop 0
	global_load_lds_dwordx4 v194, s[42:43]
	s_add_u32 m0, m0, 0x400
	s_nop 0
	global_load_lds_dwordx4 v201, s[42:43]
	s_add_u32 m0, m0, 0x400
	s_nop 0
	global_load_lds_dwordx4 v194, s[44:45]
	s_add_u32 m0, m0, 0x400
	s_nop 0
	global_load_lds_dwordx4 v201, s[44:45]
	s_add_u32 m0, m0, 0x3400
	s_nop 0
	global_load_lds_dwordx4 v206, s[46:47]
	s_add_u32 m0, m0, 0x400
	s_nop 0
	global_load_lds_dwordx4 v212, s[46:47]
	s_add_u32 m0, m0, 0x400
	s_nop 0
	global_load_lds_dwordx4 v206, s[24:25]
	s_add_u32 m0, m0, 0x400
	s_nop 0
	global_load_lds_dwordx4 v212, s[24:25]
	s_waitcnt lgkmcnt(6)
	v_mfma_f32_32x32x16_bf16 v[48:63], v[144:147], v[182:185], v[48:63]
	s_waitcnt lgkmcnt(5)
	v_mfma_f32_32x32x16_bf16 v[32:47], v[186:189], v[182:185], v[32:47]
	s_waitcnt lgkmcnt(4)
	v_mfma_f32_32x32x16_bf16 v[16:31], v[144:147], v[190:193], v[16:31]
	v_mfma_f32_32x32x16_bf16 v[0:15], v[186:189], v[190:193], v[0:15]
	v_xor_b32_e32 v242, 64, v213
	v_xor_b32_e32 v243, 64, v214
	ds_read_b128 v[144:147], v243
	ds_read_b128 v[182:185], v242
	ds_read_b128 v[186:189], v243 offset:4096
	ds_read_b128 v[190:193], v242 offset:4096
	s_waitcnt lgkmcnt(6)
	v_mfma_f32_32x32x16_bf16 v[48:63], v[202:205], v[208:211], v[48:63]
	s_waitcnt lgkmcnt(5)
	v_mfma_f32_32x32x16_bf16 v[32:47], v[234:237], v[208:211], v[32:47]
	s_waitcnt lgkmcnt(4)
	v_mfma_f32_32x32x16_bf16 v[16:31], v[202:205], v[238:241], v[16:31]
	v_mfma_f32_32x32x16_bf16 v[0:15], v[234:237], v[238:241], v[0:15]
	v_xor_b32_e32 v242, 96, v213
	v_xor_b32_e32 v243, 96, v214
	ds_read_b128 v[202:205], v243
	ds_read_b128 v[208:211], v242
	ds_read_b128 v[234:237], v243 offset:4096
	ds_read_b128 v[238:241], v242 offset:4096
	s_waitcnt lgkmcnt(6)
	v_mfma_f32_32x32x16_bf16 v[48:63], v[144:147], v[182:185], v[48:63]
	s_waitcnt lgkmcnt(5)
	v_mfma_f32_32x32x16_bf16 v[32:47], v[186:189], v[182:185], v[32:47]
	s_waitcnt lgkmcnt(4)
	v_mfma_f32_32x32x16_bf16 v[16:31], v[144:147], v[190:193], v[16:31]
	v_mfma_f32_32x32x16_bf16 v[0:15], v[186:189], v[190:193], v[0:15]
	s_waitcnt lgkmcnt(2)
	v_mfma_f32_32x32x16_bf16 v[48:63], v[202:205], v[208:211], v[48:63]
	s_waitcnt lgkmcnt(1)
	v_mfma_f32_32x32x16_bf16 v[32:47], v[234:237], v[208:211], v[32:47]
	s_waitcnt lgkmcnt(0)
	v_mfma_f32_32x32x16_bf16 v[16:31], v[202:205], v[238:241], v[16:31]
	v_mfma_f32_32x32x16_bf16 v[0:15], v[234:237], v[238:241], v[0:15]
	v_xor_b32_e32 v213, 0x8000, v213
	v_xor_b32_e32 v214, 0x8000, v214
	s_xor_b32 s49, s49, 0x8000
	s_add_u32 s42, s42, 128
	s_addc_u32 s43, s43, 0
	s_add_u32 s44, s44, 128
	s_addc_u32 s45, s45, 0
	s_add_u32 s46, s46, 128
	s_addc_u32 s47, s47, 0
	s_add_u32 s24, s24, 128
	s_addc_u32 s25, s25, 0
	s_add_u32 s2, s2, 1
	s_waitcnt vmcnt(0)
	s_cmp_lt_u32 s2, s41
	s_barrier
	s_cbranch_scc1 .LBB0_128
.Lp4b_tail:
	ds_read_b128 v[144:147], v214
	ds_read_b128 v[182:185], v213
	ds_read_b128 v[186:189], v214 offset:4096
	ds_read_b128 v[190:193], v213 offset:4096
	v_xor_b32_e32 v242, 32, v213
	v_xor_b32_e32 v243, 32, v214
	ds_read_b128 v[202:205], v243
	ds_read_b128 v[208:211], v242
	ds_read_b128 v[234:237], v243 offset:4096
	ds_read_b128 v[238:241], v242 offset:4096
	s_waitcnt lgkmcnt(6)
	v_mfma_f32_32x32x16_bf16 v[48:63], v[144:147], v[182:185], v[48:63]
	s_waitcnt lgkmcnt(5)
	v_mfma_f32_32x32x16_bf16 v[32:47], v[186:189], v[182:185], v[32:47]
	s_waitcnt lgkmcnt(4)
	v_mfma_f32_32x32x16_bf16 v[16:31], v[144:147], v[190:193], v[16:31]
	v_mfma_f32_32x32x16_bf16 v[0:15], v[186:189], v[190:193], v[0:15]
	v_xor_b32_e32 v242, 64, v213
	v_xor_b32_e32 v243, 64, v214
	ds_read_b128 v[144:147], v243
	ds_read_b128 v[182:185], v242
	ds_read_b128 v[186:189], v243 offset:4096
	ds_read_b128 v[190:193], v242 offset:4096
	s_waitcnt lgkmcnt(6)
	v_mfma_f32_32x32x16_bf16 v[48:63], v[202:205], v[208:211], v[48:63]
	s_waitcnt lgkmcnt(5)
	v_mfma_f32_32x32x16_bf16 v[32:47], v[234:237], v[208:211], v[32:47]
	s_waitcnt lgkmcnt(4)
	v_mfma_f32_32x32x16_bf16 v[16:31], v[202:205], v[238:241], v[16:31]
	v_mfma_f32_32x32x16_bf16 v[0:15], v[234:237], v[238:241], v[0:15]
	v_xor_b32_e32 v242, 96, v213
	v_xor_b32_e32 v243, 96, v214
	ds_read_b128 v[202:205], v243
	ds_read_b128 v[208:211], v242
	ds_read_b128 v[234:237], v243 offset:4096
	ds_read_b128 v[238:241], v242 offset:4096
	s_waitcnt lgkmcnt(6)
	v_mfma_f32_32x32x16_bf16 v[48:63], v[144:147], v[182:185], v[48:63]
	s_waitcnt lgkmcnt(5)
	v_mfma_f32_32x32x16_bf16 v[32:47], v[186:189], v[182:185], v[32:47]
	s_waitcnt lgkmcnt(4)
	v_mfma_f32_32x32x16_bf16 v[16:31], v[144:147], v[190:193], v[16:31]
	v_mfma_f32_32x32x16_bf16 v[0:15], v[186:189], v[190:193], v[0:15]
	s_waitcnt lgkmcnt(2)
	v_mfma_f32_32x32x16_bf16 v[48:63], v[202:205], v[208:211], v[48:63]
	s_waitcnt lgkmcnt(1)
	v_mfma_f32_32x32x16_bf16 v[32:47], v[234:237], v[208:211], v[32:47]
	s_waitcnt lgkmcnt(0)
	v_mfma_f32_32x32x16_bf16 v[16:31], v[202:205], v[238:241], v[16:31]
	v_mfma_f32_32x32x16_bf16 v[0:15], v[234:237], v[238:241], v[0:15]
	v_xor_b32_e32 v213, 0x8000, v213
	v_xor_b32_e32 v214, 0x8000, v214
	s_add_u32 s2, s2, 1
	s_waitcnt vmcnt(0)
	s_barrier
	s_bitcmp1_b32 s2, 0
	s_cselect_b32 s2, 0x9000, 0
	s_add_i32 s2, s2, 0
	v_cvt_pk_bf16_f32 v88, v88, v89
	v_add3_u32 v89, s2, v122, v120
	v_cvt_pk_bf16_f32 v147, v74, v75
	v_cvt_pk_bf16_f32 v146, v76, v77
	v_cvt_pk_bf16_f32 v145, v78, v79
	v_cvt_pk_bf16_f32 v144, v80, v81
	v_cvt_pk_bf16_f32 v143, v82, v83
	v_cvt_pk_bf16_f32 v142, v84, v85
	v_cvt_pk_bf16_f32 v141, v86, v87
	v_cvt_pk_bf16_f32 v87, v90, v91
	v_cvt_pk_bf16_f32 v86, v92, v93
	v_cvt_pk_bf16_f32 v85, v94, v95
	v_cvt_pk_bf16_f32 v84, v96, v97
	v_cvt_pk_bf16_f32 v83, v98, v99
	v_cvt_pk_bf16_f32 v82, v100, v101
	v_cvt_pk_bf16_f32 v81, v102, v103
	v_cvt_pk_bf16_f32 v80, v104, v105
	v_cvt_pk_bf16_f32 v79, v106, v107
	v_cvt_pk_bf16_f32 v78, v108, v109
	v_cvt_pk_bf16_f32 v77, v110, v111
	v_cvt_pk_bf16_f32 v76, v112, v113
	v_cvt_pk_bf16_f32 v75, v114, v115
	v_add3_u32 v114, s2, v121, v120
	v_cvt_pk_bf16_f32 v74, v116, v117
	v_cvt_pk_bf16_f32 v73, v118, v119
	v_cvt_pk_bf16_f32 v72, v123, v124
	v_cvt_pk_bf16_f32 v71, v125, v126
	v_cvt_pk_bf16_f32 v70, v127, v128
	v_cvt_pk_bf16_f32 v69, v129, v130
	v_cvt_pk_bf16_f32 v68, v131, v132
	v_cvt_pk_bf16_f32 v67, v133, v134
	v_cvt_pk_bf16_f32 v66, v135, v136
	v_cvt_pk_bf16_f32 v65, v137, v138
	v_cvt_pk_bf16_f32 v64, v139, v140
	s_add_i32 s20, s20, 1
	v_readlane_b32 s24, v250, 43
	s_cmp_eq_u32 s20, 3
	v_readlane_b32 s25, v250, 44
	v_readlane_b32 s26, v250, 45
	v_readlane_b32 s27, v250, 46
	v_readlane_b32 s28, v250, 47
	v_readlane_b32 s29, v250, 48
	v_readlane_b32 s30, v250, 49
	v_readlane_b32 s31, v250, 50
	s_barrier
	v_lshlrev_b32_e32 v90, 16, v175
	v_lshlrev_b32_e32 v92, 16, v147
	v_and_b32_e32 v91, 0xffff0000, v175
	v_and_b32_e32 v93, 0xffff0000, v147
	s_nop 6
	v_fma_f32 v48, v48, v92, v90
	v_fma_f32 v49, v49, v93, v91
	v_lshlrev_b32_e32 v90, 16, v146
	v_cvt_pk_bf16_f32 v175, v48, v49
	v_lshlrev_b32_e32 v48, 16, v178
	v_and_b32_e32 v49, 0xffff0000, v178
	v_and_b32_e32 v91, 0xffff0000, v146
	v_pk_fma_f32 v[48:49], v[50:51], v[90:91], v[48:49]
	v_lshlrev_b32_e32 v50, 16, v145
	v_cvt_pk_bf16_f32 v178, v48, v49
	v_lshlrev_b32_e32 v48, 16, v176
	v_and_b32_e32 v49, 0xffff0000, v176
	v_and_b32_e32 v51, 0xffff0000, v145
	v_pk_fma_f32 v[48:49], v[52:53], v[50:51], v[48:49]
	v_lshlrev_b32_e32 v50, 16, v144
	v_cvt_pk_bf16_f32 v176, v48, v49
	v_lshlrev_b32_e32 v48, 16, v174
	v_and_b32_e32 v49, 0xffff0000, v174
	v_and_b32_e32 v51, 0xffff0000, v144
	v_pk_fma_f32 v[48:49], v[54:55], v[50:51], v[48:49]
	v_lshlrev_b32_e32 v50, 16, v143
	v_cvt_pk_bf16_f32 v174, v48, v49
	v_lshlrev_b32_e32 v48, 16, v180
	v_and_b32_e32 v49, 0xffff0000, v180
	v_and_b32_e32 v51, 0xffff0000, v143
	v_pk_fma_f32 v[48:49], v[56:57], v[50:51], v[48:49]
	v_lshlrev_b32_e32 v50, 16, v142
	v_cvt_pk_bf16_f32 v180, v48, v49
	v_lshlrev_b32_e32 v48, 16, v179
	v_and_b32_e32 v49, 0xffff0000, v179
	v_and_b32_e32 v51, 0xffff0000, v142
	v_pk_fma_f32 v[48:49], v[58:59], v[50:51], v[48:49]
	v_lshlrev_b32_e32 v50, 16, v141
	v_cvt_pk_bf16_f32 v179, v48, v49
	v_lshlrev_b32_e32 v48, 16, v177
	v_and_b32_e32 v49, 0xffff0000, v177
	v_and_b32_e32 v51, 0xffff0000, v141
	v_pk_fma_f32 v[48:49], v[60:61], v[50:51], v[48:49]
	v_lshlrev_b32_e32 v50, 16, v88
	v_cvt_pk_bf16_f32 v177, v48, v49
	v_lshlrev_b32_e32 v48, 16, v173
	v_and_b32_e32 v49, 0xffff0000, v173
	v_and_b32_e32 v51, 0xffff0000, v88
	v_pk_fma_f32 v[48:49], v[62:63], v[50:51], v[48:49]
	v_lshlrev_b32_e32 v50, 16, v87
	v_cvt_pk_bf16_f32 v173, v48, v49
	v_lshlrev_b32_e32 v48, 16, v169
	v_and_b32_e32 v49, 0xffff0000, v169
	v_and_b32_e32 v51, 0xffff0000, v87
	v_pk_fma_f32 v[32:33], v[32:33], v[50:51], v[48:49]
	v_lshlrev_b32_e32 v48, 16, v86
	v_cvt_pk_bf16_f32 v169, v32, v33
	v_lshlrev_b32_e32 v32, 16, v171
	v_and_b32_e32 v33, 0xffff0000, v171
	v_and_b32_e32 v49, 0xffff0000, v86
	v_pk_fma_f32 v[32:33], v[34:35], v[48:49], v[32:33]
	v_lshlrev_b32_e32 v34, 16, v85
	v_cvt_pk_bf16_f32 v171, v32, v33
	v_lshlrev_b32_e32 v32, 16, v170
	v_and_b32_e32 v33, 0xffff0000, v170
	v_and_b32_e32 v35, 0xffff0000, v85
	v_pk_fma_f32 v[32:33], v[36:37], v[34:35], v[32:33]
	v_lshlrev_b32_e32 v34, 16, v84
	v_cvt_pk_bf16_f32 v170, v32, v33
	v_lshlrev_b32_e32 v32, 16, v168
	v_and_b32_e32 v33, 0xffff0000, v168
	v_and_b32_e32 v35, 0xffff0000, v84
	v_pk_fma_f32 v[32:33], v[38:39], v[34:35], v[32:33]
	v_lshlrev_b32_e32 v34, 16, v83
	v_cvt_pk_bf16_f32 v168, v32, v33
	v_lshlrev_b32_e32 v32, 16, v167
	v_and_b32_e32 v33, 0xffff0000, v167
	v_and_b32_e32 v35, 0xffff0000, v83
	v_fma_f32 v32, v40, v34, v32
	v_fma_f32 v33, v41, v35, v33
	v_lshlrev_b32_e32 v34, 16, v82
	v_cvt_pk_bf16_f32 v167, v32, v33
	v_lshlrev_b32_e32 v32, 16, v166
	v_and_b32_e32 v33, 0xffff0000, v166
	v_and_b32_e32 v35, 0xffff0000, v82
	v_pk_fma_f32 v[32:33], v[42:43], v[34:35], v[32:33]
	v_lshlrev_b32_e32 v34, 16, v81
	v_cvt_pk_bf16_f32 v166, v32, v33
	v_lshlrev_b32_e32 v32, 16, v165
	v_and_b32_e32 v33, 0xffff0000, v165
	v_and_b32_e32 v35, 0xffff0000, v81
	v_pk_fma_f32 v[32:33], v[44:45], v[34:35], v[32:33]
	v_lshlrev_b32_e32 v34, 16, v80
	v_cvt_pk_bf16_f32 v165, v32, v33
	v_lshlrev_b32_e32 v32, 16, v164
	v_and_b32_e32 v33, 0xffff0000, v164
	v_and_b32_e32 v35, 0xffff0000, v80
	v_pk_fma_f32 v[32:33], v[46:47], v[34:35], v[32:33]
	v_lshlrev_b32_e32 v34, 16, v79
	v_cvt_pk_bf16_f32 v164, v32, v33
	v_lshlrev_b32_e32 v32, 16, v161
	v_and_b32_e32 v33, 0xffff0000, v161
	v_and_b32_e32 v35, 0xffff0000, v79
	v_pk_fma_f32 v[16:17], v[16:17], v[34:35], v[32:33]
	v_lshlrev_b32_e32 v32, 16, v78
	v_cvt_pk_bf16_f32 v161, v16, v17
	v_lshlrev_b32_e32 v16, 16, v163
	v_and_b32_e32 v17, 0xffff0000, v163
	v_and_b32_e32 v33, 0xffff0000, v78
	v_pk_fma_f32 v[16:17], v[18:19], v[32:33], v[16:17]
	v_lshlrev_b32_e32 v18, 16, v77
	v_cvt_pk_bf16_f32 v163, v16, v17
	v_lshlrev_b32_e32 v16, 16, v162
	v_and_b32_e32 v17, 0xffff0000, v162
	v_and_b32_e32 v19, 0xffff0000, v77
	v_pk_fma_f32 v[16:17], v[20:21], v[18:19], v[16:17]
	v_lshlrev_b32_e32 v18, 16, v76
	v_cvt_pk_bf16_f32 v162, v16, v17
	v_lshlrev_b32_e32 v16, 16, v160
	v_and_b32_e32 v17, 0xffff0000, v160
	v_and_b32_e32 v19, 0xffff0000, v76
	v_pk_fma_f32 v[16:17], v[22:23], v[18:19], v[16:17]
	v_lshlrev_b32_e32 v18, 16, v75
	v_cvt_pk_bf16_f32 v160, v16, v17
	v_lshlrev_b32_e32 v16, 16, v159
	v_and_b32_e32 v17, 0xffff0000, v159
	v_and_b32_e32 v19, 0xffff0000, v75
	v_fma_f32 v16, v24, v18, v16
	v_fma_f32 v17, v25, v19, v17
	v_lshlrev_b32_e32 v18, 16, v74
	v_cvt_pk_bf16_f32 v159, v16, v17
	v_lshlrev_b32_e32 v16, 16, v158
	v_and_b32_e32 v17, 0xffff0000, v158
	v_and_b32_e32 v19, 0xffff0000, v74
	v_pk_fma_f32 v[16:17], v[26:27], v[18:19], v[16:17]
	v_lshlrev_b32_e32 v18, 16, v73
	v_cvt_pk_bf16_f32 v158, v16, v17
	v_lshlrev_b32_e32 v16, 16, v157
	v_and_b32_e32 v17, 0xffff0000, v157
	v_and_b32_e32 v19, 0xffff0000, v73
	v_pk_fma_f32 v[16:17], v[28:29], v[18:19], v[16:17]
	v_lshlrev_b32_e32 v18, 16, v72
	v_cvt_pk_bf16_f32 v157, v16, v17
	v_lshlrev_b32_e32 v16, 16, v156
	v_and_b32_e32 v17, 0xffff0000, v156
	v_and_b32_e32 v19, 0xffff0000, v72
	v_pk_fma_f32 v[16:17], v[30:31], v[18:19], v[16:17]
	v_lshlrev_b32_e32 v18, 16, v71
	v_cvt_pk_bf16_f32 v156, v16, v17
	v_lshlrev_b32_e32 v16, 16, v153
	v_and_b32_e32 v17, 0xffff0000, v153
	v_and_b32_e32 v19, 0xffff0000, v71
	v_pk_fma_f32 v[0:1], v[0:1], v[18:19], v[16:17]
	v_lshlrev_b32_e32 v16, 16, v70
	v_cvt_pk_bf16_f32 v153, v0, v1
	v_lshlrev_b32_e32 v0, 16, v155
	v_and_b32_e32 v1, 0xffff0000, v155
	v_and_b32_e32 v17, 0xffff0000, v70
	v_pk_fma_f32 v[0:1], v[2:3], v[16:17], v[0:1]
	v_lshlrev_b32_e32 v2, 16, v69
	v_cvt_pk_bf16_f32 v155, v0, v1
	v_lshlrev_b32_e32 v0, 16, v154
	v_and_b32_e32 v1, 0xffff0000, v154
	v_and_b32_e32 v3, 0xffff0000, v69
	v_pk_fma_f32 v[0:1], v[4:5], v[2:3], v[0:1]
	v_lshlrev_b32_e32 v2, 16, v68
	v_cvt_pk_bf16_f32 v154, v0, v1
	v_lshlrev_b32_e32 v0, 16, v152
	v_and_b32_e32 v1, 0xffff0000, v152
	v_and_b32_e32 v3, 0xffff0000, v68
	v_pk_fma_f32 v[0:1], v[6:7], v[2:3], v[0:1]
	v_lshlrev_b32_e32 v2, 16, v67
	v_cvt_pk_bf16_f32 v152, v0, v1
	v_lshlrev_b32_e32 v0, 16, v151
	v_and_b32_e32 v1, 0xffff0000, v151
	v_and_b32_e32 v3, 0xffff0000, v67
	v_pk_fma_f32 v[0:1], v[8:9], v[2:3], v[0:1]
	v_lshlrev_b32_e32 v2, 16, v66
	v_cvt_pk_bf16_f32 v151, v0, v1
	v_lshlrev_b32_e32 v0, 16, v150
	v_and_b32_e32 v1, 0xffff0000, v150
	v_and_b32_e32 v3, 0xffff0000, v66
	v_pk_fma_f32 v[0:1], v[10:11], v[2:3], v[0:1]
	v_lshlrev_b32_e32 v2, 16, v65
	v_cvt_pk_bf16_f32 v150, v0, v1
	v_lshlrev_b32_e32 v0, 16, v149
	v_and_b32_e32 v1, 0xffff0000, v149
	v_and_b32_e32 v3, 0xffff0000, v65
	v_pk_fma_f32 v[0:1], v[12:13], v[2:3], v[0:1]
	v_lshlrev_b32_e32 v2, 16, v64
	v_cvt_pk_bf16_f32 v149, v0, v1
	v_lshlrev_b32_e32 v0, 16, v148
	v_and_b32_e32 v1, 0xffff0000, v148
	v_and_b32_e32 v3, 0xffff0000, v64
	v_pk_fma_f32 v[0:1], v[14:15], v[2:3], v[0:1]
	s_nop 0
	v_cvt_pk_bf16_f32 v148, v0, v1
	s_cbranch_scc0 .LBB0_123
	v_mov_b32_e32 v64, v200
	v_lshlrev_b32_e32 v0, 16, v175
	v_and_b32_e32 v66, 31, v64
	v_lshrrev_b32_e32 v67, 1, v64
	v_and_b32_e32 v65, 64, v64
	v_and_or_b32 v66, v67, s40, v66
	v_lshrrev_b32_e32 v67, 3, v64
	v_and_b32_e32 v1, 0xffff0000, v175
	v_lshlrev_b32_e32 v2, 16, v178
	v_and_b32_e32 v3, 0xffff0000, v178
	v_and_or_b32 v65, v67, 4, v65
	v_lshlrev_b32_e32 v4, 16, v176
	v_and_b32_e32 v5, 0xffff0000, v176
	v_lshlrev_b32_e32 v6, 16, v174
	v_and_b32_e32 v7, 0xffff0000, v174
	v_mul_lo_u32 v66, v66, s48
	v_cvt_pk_bf16_f32 v0, v0, v1
	v_cvt_pk_bf16_f32 v1, v2, v3
	v_lshlrev_b32_e32 v2, 1, v65
	v_lshlrev_b32_e32 v8, 16, v180
	v_and_b32_e32 v9, 0xffff0000, v180
	v_lshlrev_b32_e32 v10, 16, v179
	v_and_b32_e32 v11, 0xffff0000, v179
	v_lshlrev_b32_e32 v12, 16, v177
	v_and_b32_e32 v13, 0xffff0000, v177
	v_lshlrev_b32_e32 v14, 16, v173
	v_and_b32_e32 v15, 0xffff0000, v173
	v_add3_u32 v65, 0, v66, v2
	v_cvt_pk_bf16_f32 v2, v4, v5
	v_cvt_pk_bf16_f32 v3, v6, v7
	v_lshlrev_b32_e32 v16, 16, v169
	v_and_b32_e32 v17, 0xffff0000, v169
	v_lshlrev_b32_e32 v18, 16, v171
	v_and_b32_e32 v19, 0xffff0000, v171
	v_lshlrev_b32_e32 v20, 16, v170
	v_and_b32_e32 v21, 0xffff0000, v170
	v_lshlrev_b32_e32 v22, 16, v168
	v_and_b32_e32 v23, 0xffff0000, v168
	ds_write2_b64 v65, v[0:1], v[2:3] offset1:2
	v_cvt_pk_bf16_f32 v0, v8, v9
	v_cvt_pk_bf16_f32 v1, v10, v11
	v_cvt_pk_bf16_f32 v2, v12, v13
	v_cvt_pk_bf16_f32 v3, v14, v15
	v_lshlrev_b32_e32 v24, 16, v167
	v_and_b32_e32 v25, 0xffff0000, v167
	v_lshlrev_b32_e32 v26, 16, v166
	v_and_b32_e32 v27, 0xffff0000, v166
	v_lshlrev_b32_e32 v28, 16, v165
	v_and_b32_e32 v29, 0xffff0000, v165
	v_lshlrev_b32_e32 v30, 16, v164
	v_and_b32_e32 v31, 0xffff0000, v164
	ds_write2_b64 v65, v[0:1], v[2:3] offset0:4 offset1:6
	v_cvt_pk_bf16_f32 v0, v16, v17
	v_cvt_pk_bf16_f32 v1, v18, v19
	v_cvt_pk_bf16_f32 v2, v20, v21
	v_cvt_pk_bf16_f32 v3, v22, v23
	v_lshlrev_b32_e32 v32, 16, v161
	v_and_b32_e32 v33, 0xffff0000, v161
	v_lshlrev_b32_e32 v34, 16, v163
	v_and_b32_e32 v35, 0xffff0000, v163
	v_lshlrev_b32_e32 v36, 16, v162
	v_and_b32_e32 v37, 0xffff0000, v162
	v_lshlrev_b32_e32 v38, 16, v160
	v_and_b32_e32 v39, 0xffff0000, v160
	ds_write2_b64 v65, v[0:1], v[2:3] offset0:8 offset1:10
	v_cvt_pk_bf16_f32 v0, v24, v25
	v_cvt_pk_bf16_f32 v1, v26, v27
	v_cvt_pk_bf16_f32 v2, v28, v29
	v_cvt_pk_bf16_f32 v3, v30, v31
	v_lshlrev_b32_e32 v40, 16, v159
	v_and_b32_e32 v41, 0xffff0000, v159
	v_lshlrev_b32_e32 v42, 16, v158
	v_and_b32_e32 v43, 0xffff0000, v158
	v_lshlrev_b32_e32 v44, 16, v157
	v_and_b32_e32 v45, 0xffff0000, v157
	v_lshlrev_b32_e32 v46, 16, v156
	v_and_b32_e32 v47, 0xffff0000, v156
	ds_write2_b64 v65, v[0:1], v[2:3] offset0:12 offset1:14
	v_cvt_pk_bf16_f32 v0, v32, v33
	v_cvt_pk_bf16_f32 v1, v34, v35
	v_cvt_pk_bf16_f32 v2, v36, v37
	v_cvt_pk_bf16_f32 v3, v38, v39
	v_add_u32_e32 v4, 0x2000, v65
	v_lshlrev_b32_e32 v48, 16, v153
	v_and_b32_e32 v49, 0xffff0000, v153
	v_lshlrev_b32_e32 v50, 16, v155
	v_and_b32_e32 v51, 0xffff0000, v155
	v_lshlrev_b32_e32 v52, 16, v154
	v_and_b32_e32 v53, 0xffff0000, v154
	v_lshlrev_b32_e32 v54, 16, v152
	v_and_b32_e32 v55, 0xffff0000, v152
	ds_write2_b64 v4, v[0:1], v[2:3] offset0:64 offset1:66
	v_cvt_pk_bf16_f32 v0, v40, v41
	v_cvt_pk_bf16_f32 v1, v42, v43
	v_cvt_pk_bf16_f32 v2, v44, v45
	v_cvt_pk_bf16_f32 v3, v46, v47
	v_lshlrev_b32_e32 v56, 16, v151
	v_and_b32_e32 v57, 0xffff0000, v151
	v_lshlrev_b32_e32 v58, 16, v150
	v_and_b32_e32 v59, 0xffff0000, v150
	v_lshlrev_b32_e32 v60, 16, v149
	v_and_b32_e32 v61, 0xffff0000, v149
	v_lshlrev_b32_e32 v62, 16, v148
	v_and_b32_e32 v63, 0xffff0000, v148
	ds_write2_b64 v4, v[0:1], v[2:3] offset0:68 offset1:70
	v_cvt_pk_bf16_f32 v0, v48, v49
	v_cvt_pk_bf16_f32 v1, v50, v51
	v_cvt_pk_bf16_f32 v2, v52, v53
	v_cvt_pk_bf16_f32 v3, v54, v55
	s_add_u32 s2, s24, s14
	ds_write2_b64 v4, v[0:1], v[2:3] offset0:72 offset1:74
	v_cvt_pk_bf16_f32 v0, v56, v57
	v_cvt_pk_bf16_f32 v1, v58, v59
	v_cvt_pk_bf16_f32 v2, v60, v61
	v_cvt_pk_bf16_f32 v3, v62, v63
	s_addc_u32 s5, s25, 0
	s_lshl_b32 s4, s4, 1
	ds_write2_b64 v4, v[0:1], v[2:3] offset0:76 offset1:78
	v_lshlrev_b32_e32 v0, 4, v64
	s_add_u32 s4, s2, s4
	v_and_b32_e32 v196, 0xf0, v0
	s_addc_u32 s5, s5, 0
	v_add_u32_e32 v4, 0, v196
	v_ashrrev_i32_e32 v8, 4, v64
	v_lshl_add_u64 v[6:7], s[4:5], 0, v[196:197]
	v_mad_u64_u32 v[0:1], s[4:5], v8, s48, v[4:5]
	s_waitcnt lgkmcnt(0)
	s_barrier
	ds_read_b128 v[0:3], v0
	v_ashrrev_i32_e32 v9, 31, v8
	v_lshlrev_b64 v[8:9], 11, v[8:9]
	v_lshl_add_u64 v[8:9], v[6:7], 0, v[8:9]
	s_add_i32 s0, s0, 1
	s_waitcnt lgkmcnt(0)
	global_store_dwordx4 v[8:9], v[0:3], off
	s_mul_i32 s2, s0, s1
	s_add_i32 s2, s2, s39
	v_add_u32_e32 v0, 0x100, v64
	v_ashrrev_i32_e32 v8, 4, v0
	v_mad_u64_u32 v[0:1], s[4:5], v8, s48, v[4:5]
	ds_read_b128 v[0:3], v0
	v_ashrrev_i32_e32 v9, 31, v8
	v_lshlrev_b64 v[8:9], 11, v[8:9]
	v_lshl_add_u64 v[8:9], v[6:7], 0, v[8:9]
	s_cmpk_gt_u32 s2, 0x7f
	s_waitcnt lgkmcnt(0)
	global_store_dwordx4 v[8:9], v[0:3], off
	s_nop 1
	v_add_u32_e32 v0, 0x200, v64
	v_ashrrev_i32_e32 v8, 4, v0
	v_mad_u64_u32 v[0:1], s[4:5], v8, s48, v[4:5]
	ds_read_b128 v[0:3], v0
	v_ashrrev_i32_e32 v9, 31, v8
	v_lshlrev_b64 v[8:9], 11, v[8:9]
	v_lshl_add_u64 v[8:9], v[6:7], 0, v[8:9]
	s_waitcnt lgkmcnt(0)
	global_store_dwordx4 v[8:9], v[0:3], off
	s_nop 1
	v_add_u32_e32 v0, 0x300, v64
	v_ashrrev_i32_e32 v8, 4, v0
	v_mad_u64_u32 v[0:1], s[4:5], v8, s48, v[4:5]
	ds_read_b128 v[0:3], v0
	v_ashrrev_i32_e32 v9, 31, v8
	v_lshlrev_b64 v[8:9], 11, v[8:9]
	v_lshl_add_u64 v[8:9], v[6:7], 0, v[8:9]
	s_waitcnt lgkmcnt(0)
	global_store_dwordx4 v[8:9], v[0:3], off
	s_nop 1
	v_add_u32_e32 v0, 0x400, v64
	v_ashrrev_i32_e32 v8, 4, v0
	v_mad_u64_u32 v[0:1], s[4:5], v8, s48, v[4:5]
	ds_read_b128 v[0:3], v0
	v_ashrrev_i32_e32 v9, 31, v8
	v_lshlrev_b64 v[8:9], 11, v[8:9]
	v_lshl_add_u64 v[8:9], v[6:7], 0, v[8:9]
	s_waitcnt lgkmcnt(0)
	global_store_dwordx4 v[8:9], v[0:3], off
	s_nop 1
	v_add_u32_e32 v0, 0x500, v64
	v_ashrrev_i32_e32 v8, 4, v0
	v_mad_u64_u32 v[0:1], s[4:5], v8, s48, v[4:5]
	ds_read_b128 v[0:3], v0
	v_ashrrev_i32_e32 v9, 31, v8
	v_lshlrev_b64 v[8:9], 11, v[8:9]
	v_lshl_add_u64 v[8:9], v[6:7], 0, v[8:9]
	s_waitcnt lgkmcnt(0)
	global_store_dwordx4 v[8:9], v[0:3], off
	s_nop 1
	v_add_u32_e32 v0, 0x600, v64
	v_ashrrev_i32_e32 v8, 4, v0
	v_mad_u64_u32 v[0:1], s[4:5], v8, s48, v[4:5]
	ds_read_b128 v[0:3], v0
	v_ashrrev_i32_e32 v9, 31, v8
	v_lshlrev_b64 v[8:9], 11, v[8:9]
	v_lshl_add_u64 v[8:9], v[6:7], 0, v[8:9]
	s_waitcnt lgkmcnt(0)
	global_store_dwordx4 v[8:9], v[0:3], off
	s_nop 1
	v_add_u32_e32 v0, 0x700, v64
	v_ashrrev_i32_e32 v8, 4, v0
	v_mad_u64_u32 v[0:1], s[4:5], v8, s48, v[4:5]
	ds_read_b128 v[0:3], v0
	v_ashrrev_i32_e32 v9, 31, v8
	v_lshlrev_b64 v[4:5], 11, v[8:9]
	v_lshl_add_u64 v[4:5], v[6:7], 0, v[4:5]
	s_waitcnt lgkmcnt(0)
	global_store_dwordx4 v[4:5], v[0:3], off
	s_barrier
	s_cbranch_scc0 .LBB0_122
